# attention loop heads placed at 48 / 16 mod 64 (same phases as the earlier best build); DPP preambles included
# speedup vs baseline: 1.0144x; 1.0009x over previous
.LBB0_505:
	v_add_f32_e32 v16, 0, v32
	v_add_f32_e32 v16, v33, v16
	v_add_f32_e32 v17, 0, v40
	v_add_f32_e32 v16, v34, v16
	v_add_f32_e32 v17, v41, v17
	v_add_f32_e32 v16, v35, v16
	v_add_f32_e32 v17, v42, v17
	v_add_f32_e32 v16, v36, v16
	v_add_f32_e32 v17, v43, v17
	v_add_f32_e32 v16, v37, v16
	v_add_f32_e32 v17, v44, v17
	v_add_f32_e32 v16, v38, v16
	v_add_f32_e32 v17, v45, v17
	v_add_f32_e32 v16, v39, v16
	v_add_f32_e32 v17, v46, v17
	v_add_f32_e32 v16, 0, v16
	v_add_f32_e32 v17, v47, v17
	v_add_f32_e32 v18, 0, v48
	v_add_f32_e32 v16, v17, v16
	v_add_f32_e32 v17, 0, v56
	v_add_f32_e32 v18, v49, v18
	v_add_f32_e32 v17, v57, v17
	v_add_f32_e32 v18, v50, v18
	v_add_f32_e32 v17, v58, v17
	v_add_f32_e32 v18, v51, v18
	v_add_f32_e32 v17, v59, v17
	v_add_f32_e32 v18, v52, v18
	v_add_f32_e32 v17, v60, v17
	v_add_f32_e32 v18, v53, v18
	v_add_f32_e32 v17, v61, v17
	v_add_f32_e32 v18, v54, v18
	s_waitcnt vmcnt(0)
	ds_write_b64 v216, v[64:65] offset:18432
	s_waitcnt lgkmcnt(0)
	ds_write_b64 v216, v[68:69] offset:27648
	ds_write2st64_b64 v217, v[66:67], v[70:71] offset0:36 offset1:54
	ds_write_b128 v213, v[144:147]
	v_add_f32_e32 v17, v62, v17
	v_add_f32_e32 v18, v55, v18
	s_waitcnt lgkmcnt(0)
	s_barrier
	v_add_f32_e32 v17, v63, v17
	v_add_f32_e32 v16, v18, v16
	v_mov_b32_e32 v31, 0
	v_cvt_pk_bf16_f32 v160, v32, v33
	v_cvt_pk_bf16_f32 v161, v34, v35
	v_cvt_pk_bf16_f32 v162, v36, v37
	v_cvt_pk_bf16_f32 v163, v38, v39
	v_cvt_pk_bf16_f32 v148, v40, v41
	v_cvt_pk_bf16_f32 v149, v42, v43
	v_cvt_pk_bf16_f32 v150, v44, v45
	v_cvt_pk_bf16_f32 v151, v46, v47
	v_cvt_pk_bf16_f32 v152, v48, v49
	v_cvt_pk_bf16_f32 v153, v50, v51
	v_cvt_pk_bf16_f32 v154, v52, v53
	v_cvt_pk_bf16_f32 v155, v54, v55
	v_add_f32_e32 v193, v17, v16
	v_cvt_pk_bf16_f32 v156, v56, v57
	v_cvt_pk_bf16_f32 v157, v58, v59
	v_cvt_pk_bf16_f32 v158, v60, v61
	v_cvt_pk_bf16_f32 v159, v62, v63
	s_andn2_b64 vcc, exec, s[2:3]
	s_cbranch_vccnz .LBB0_512
	v_mov_b32_e32 v32, 0
	s_mov_b32 s93, 0
	s_movk_i32 s15, 0x80
	s_mov_b64 s[6:7], 0x80
	v_mov_b32_e32 v33, v32
	v_mov_b32_e32 v34, v32
	v_mov_b32_e32 v35, v32
	v_mov_b32_e32 v36, v32
	v_mov_b32_e32 v37, v32
	v_mov_b32_e32 v38, v32
	v_mov_b32_e32 v39, v32
	v_mov_b32_e32 v40, v32
	v_mov_b32_e32 v41, v32
	v_mov_b32_e32 v42, v32
	v_mov_b32_e32 v43, v32
	v_mov_b32_e32 v44, v32
	v_mov_b32_e32 v45, v32
	v_mov_b32_e32 v46, v32
	v_mov_b32_e32 v47, v32
	v_mov_b32_e32 v64, v32
	v_mov_b32_e32 v65, v32
	v_mov_b32_e32 v66, v32
	v_mov_b32_e32 v67, v32
	v_mov_b32_e32 v68, v32
	v_mov_b32_e32 v69, v32
	v_mov_b32_e32 v70, v32
	v_mov_b32_e32 v71, v32
	v_mov_b32_e32 v72, v32
	v_mov_b32_e32 v73, v32
	v_mov_b32_e32 v74, v32
	v_mov_b32_e32 v75, v32
	v_mov_b32_e32 v76, v32
	v_mov_b32_e32 v77, v32
	v_mov_b32_e32 v78, v32
	v_mov_b32_e32 v79, v32
	v_mov_b32_e32 v48, v32
	v_mov_b32_e32 v49, v32
	v_mov_b32_e32 v50, v32
	v_mov_b32_e32 v51, v32
	v_mov_b32_e32 v52, v32
	v_mov_b32_e32 v53, v32
	v_mov_b32_e32 v54, v32
	v_mov_b32_e32 v55, v32
	v_mov_b32_e32 v56, v32
	v_mov_b32_e32 v57, v32
	v_mov_b32_e32 v58, v32
	v_mov_b32_e32 v59, v32
	v_mov_b32_e32 v60, v32
	v_mov_b32_e32 v61, v32
	v_mov_b32_e32 v62, v32
	v_mov_b32_e32 v63, v32
	v_mov_b32_e32 v16, v32
	v_mov_b32_e32 v17, v32
	v_mov_b32_e32 v18, v32
	v_mov_b32_e32 v19, v32
	v_mov_b32_e32 v20, v32
	v_mov_b32_e32 v21, v32
	v_mov_b32_e32 v22, v32
	v_mov_b32_e32 v23, v32
	v_mov_b32_e32 v24, v32
	v_mov_b32_e32 v25, v32
	v_mov_b32_e32 v26, v32
	v_mov_b32_e32 v27, v32
	v_mov_b32_e32 v28, v32
	v_mov_b32_e32 v29, v32
	v_mov_b32_e32 v30, v32
	v_mov_b32_e32 v31, v32
	v_mov_b32_e32 v142, 0
	s_branch .LBB0_508
	.p2align 6
	s_nop 0
	s_nop 0
	s_nop 0
	s_nop 0
	s_nop 0
	s_nop 0
	s_nop 0
	s_nop 0
	s_nop 0
	s_nop 0
	s_nop 0
	s_nop 0

.LBB0_539:
	v_add_f32_e32 v16, 0, v32
	v_add_f32_e32 v16, v33, v16
	v_add_f32_e32 v17, 0, v40
	v_add_f32_e32 v16, v34, v16
	v_add_f32_e32 v17, v41, v17
	v_add_f32_e32 v16, v35, v16
	v_add_f32_e32 v17, v42, v17
	v_add_f32_e32 v16, v36, v16
	v_add_f32_e32 v17, v43, v17
	v_add_f32_e32 v16, v37, v16
	v_add_f32_e32 v17, v44, v17
	v_add_f32_e32 v16, v38, v16
	v_add_f32_e32 v17, v45, v17
	v_add_f32_e32 v16, v39, v16
	v_add_f32_e32 v17, v46, v17
	v_add_f32_e32 v16, 0, v16
	v_add_f32_e32 v17, v47, v17
	v_add_f32_e32 v18, 0, v48
	v_add_f32_e32 v16, v17, v16
	v_add_f32_e32 v17, 0, v56
	v_add_f32_e32 v18, v49, v18
	v_add_f32_e32 v17, v57, v17
	v_add_f32_e32 v18, v50, v18
	v_add_f32_e32 v17, v58, v17
	v_add_f32_e32 v18, v51, v18
	v_add_f32_e32 v17, v59, v17
	v_add_f32_e32 v18, v52, v18
	v_add_f32_e32 v17, v60, v17
	v_add_f32_e32 v18, v53, v18
	v_add_f32_e32 v17, v61, v17
	v_add_f32_e32 v18, v54, v18
	s_waitcnt vmcnt(0)
	ds_write_b64 v216, v[64:65] offset:18432
	s_waitcnt lgkmcnt(0)
	ds_write_b64 v216, v[68:69] offset:27648
	ds_write2st64_b64 v217, v[66:67], v[70:71] offset0:36 offset1:54
	ds_write_b128 v213, v[144:147]
	v_add_f32_e32 v17, v62, v17
	v_add_f32_e32 v18, v55, v18
	s_waitcnt lgkmcnt(0)
	s_barrier
	v_add_f32_e32 v17, v63, v17
	v_add_f32_e32 v16, v18, v16
	v_mov_b32_e32 v31, 0
	v_cvt_pk_bf16_f32 v160, v32, v33
	v_cvt_pk_bf16_f32 v161, v34, v35
	v_cvt_pk_bf16_f32 v162, v36, v37
	v_cvt_pk_bf16_f32 v163, v38, v39
	v_cvt_pk_bf16_f32 v148, v40, v41
	v_cvt_pk_bf16_f32 v149, v42, v43
	v_cvt_pk_bf16_f32 v150, v44, v45
	v_cvt_pk_bf16_f32 v151, v46, v47
	v_cvt_pk_bf16_f32 v152, v48, v49
	v_cvt_pk_bf16_f32 v153, v50, v51
	v_cvt_pk_bf16_f32 v154, v52, v53
	v_cvt_pk_bf16_f32 v155, v54, v55
	v_add_f32_e32 v193, v17, v16
	v_cvt_pk_bf16_f32 v156, v56, v57
	v_cvt_pk_bf16_f32 v157, v58, v59
	v_cvt_pk_bf16_f32 v158, v60, v61
	v_cvt_pk_bf16_f32 v159, v62, v63
	s_andn2_b64 vcc, exec, s[80:81]
	s_cbranch_vccnz .LBB0_546
	v_mov_b32_e32 v32, 0
	s_mov_b32 s77, 0
	s_movk_i32 s15, 0x80
	s_mov_b64 s[6:7], 0x80
	v_mov_b32_e32 v33, v32
	v_mov_b32_e32 v34, v32
	v_mov_b32_e32 v35, v32
	v_mov_b32_e32 v36, v32
	v_mov_b32_e32 v37, v32
	v_mov_b32_e32 v38, v32
	v_mov_b32_e32 v39, v32
	v_mov_b32_e32 v40, v32
	v_mov_b32_e32 v41, v32
	v_mov_b32_e32 v42, v32
	v_mov_b32_e32 v43, v32
	v_mov_b32_e32 v44, v32
	v_mov_b32_e32 v45, v32
	v_mov_b32_e32 v46, v32
	v_mov_b32_e32 v47, v32
	v_mov_b32_e32 v64, v32
	v_mov_b32_e32 v65, v32
	v_mov_b32_e32 v66, v32
	v_mov_b32_e32 v67, v32
	v_mov_b32_e32 v68, v32
	v_mov_b32_e32 v69, v32
	v_mov_b32_e32 v70, v32
	v_mov_b32_e32 v71, v32
	v_mov_b32_e32 v72, v32
	v_mov_b32_e32 v73, v32
	v_mov_b32_e32 v74, v32
	v_mov_b32_e32 v75, v32
	v_mov_b32_e32 v76, v32
	v_mov_b32_e32 v77, v32
	v_mov_b32_e32 v78, v32
	v_mov_b32_e32 v79, v32
	v_mov_b32_e32 v48, v32
	v_mov_b32_e32 v49, v32
	v_mov_b32_e32 v50, v32
	v_mov_b32_e32 v51, v32
	v_mov_b32_e32 v52, v32
	v_mov_b32_e32 v53, v32
	v_mov_b32_e32 v54, v32
	v_mov_b32_e32 v55, v32
	v_mov_b32_e32 v56, v32
	v_mov_b32_e32 v57, v32
	v_mov_b32_e32 v58, v32
	v_mov_b32_e32 v59, v32
	v_mov_b32_e32 v60, v32
	v_mov_b32_e32 v61, v32
	v_mov_b32_e32 v62, v32
	v_mov_b32_e32 v63, v32
	v_mov_b32_e32 v16, v32
	v_mov_b32_e32 v17, v32
	v_mov_b32_e32 v18, v32
	v_mov_b32_e32 v19, v32
	v_mov_b32_e32 v20, v32
	v_mov_b32_e32 v21, v32
	v_mov_b32_e32 v22, v32
	v_mov_b32_e32 v23, v32
	v_mov_b32_e32 v24, v32
	v_mov_b32_e32 v25, v32
	v_mov_b32_e32 v26, v32
	v_mov_b32_e32 v27, v32
	v_mov_b32_e32 v28, v32
	v_mov_b32_e32 v29, v32
	v_mov_b32_e32 v30, v32
	v_mov_b32_e32 v31, v32
	v_mov_b32_e32 v142, 0
	s_branch .LBB0_542
	.p2align 6
	s_nop 0
	s_nop 0
	s_nop 0
	s_nop 0
